# speedup vs baseline: 1.0071x; 1.0071x over previous
; #define LAS __attribute__((address_space(3)))
; __device__ __forceinline__ void attn_phase(LAS unsigned char* lds, bf16_t* Qb, const bf16_t* KVb, const bf16_t* GZ, const float* sinkp) {
;     ...
;                     float mx = __builtin_fmaxf(s0[0], s1[0]);
; #pragma unroll
;                     for (int r = 1; r < 16; ++r) { float t_; asm("v_max3_f32 %0, %1, %2, %3" : "=v"(t_) : "v"(mx), "v"(s0[r]), "v"(s1[r])); mx = t_; }
;                     mx = fmaxf(mx, __shfl_xor(mx, 32));
;                     const float mx2 = mx * SC;
;                     const bool bump = mx2 > m_run + 8.f;
;                     if (__any(bump)) {
;                         const float m_new = bump ? mx2 : m_run, alpha = __builtin_amdgcn_exp2f(m_run - m_new);
;                         m_run = m_new; l_run *= alpha;
; #pragma unroll
;                         for (int dt = 0; dt < 4; ++dt)
; #pragma unroll
;                             for (int r = 0; r < 16; ++r) o[dt][r] *= alpha;
;                     }
;     ...
;                         for (int dt = 0; dt < 4; ++dt) { va[0][dt][0] = __builtin_amdgcn_ds_read_tr16_b64_v4i16((LAS s16x4*)(Vc + vaddr[dt][0])); va[0][dt][1] = __builtin_amdgcn_ds_read_tr16_b64_v4i16((LAS s16x4*)(Vc + vaddr[dt][1])); }
.LBB0_176:
	v_add_u32_e32 v220, s3, v161
	v_add_u32_e32 v221, s3, v162
	v_add_u32_e32 v202, s3, v163
	v_add_u32_e32 v203, s3, v164
	v_add_u32_e32 v204, s3, v165
	v_add_u32_e32 v205, s3, v166
	v_add_u32_e32 v206, s3, v167
	v_add_u32_e32 v207, s3, v168
	ds_read_b64_tr_b16 v[208:209], v220 offset:16384
	ds_read_b64_tr_b16 v[210:211], v221 offset:16384
	ds_read_b64_tr_b16 v[212:213], v202 offset:16384
	ds_read_b64_tr_b16 v[214:215], v203 offset:16384
	ds_read_b64_tr_b16 v[216:217], v204 offset:16384
	ds_read_b64_tr_b16 v[218:219], v205 offset:16384
	ds_read_b64_tr_b16 v[228:229], v206 offset:16384
	ds_read_b64_tr_b16 v[230:231], v207 offset:16384
	ds_read_b64_tr_b16 v[238:239], v220 offset:20480
	ds_read_b64_tr_b16 v[240:241], v221 offset:20480
	ds_read_b64_tr_b16 v[242:243], v202 offset:20480
	ds_read_b64_tr_b16 v[244:245], v203 offset:20480
	ds_read_b64_tr_b16 v[246:247], v204 offset:20480
	ds_read_b64_tr_b16 v[248:249], v205 offset:20480
	ds_read_b64_tr_b16 v[250:251], v206 offset:20480
	ds_read_b64_tr_b16 v[252:253], v207 offset:20480
	v_max_f32_e32 v177, v64, v64
	v_max_f32_e32 v178, v80, v80
	v_max_f32_e32 v177, v178, v177
	v_max3_f32 v177, v177, v81, v65
	s_nop 0
	v_max3_f32 v177, v177, v82, v66
	s_nop 0
	v_max3_f32 v177, v177, v83, v67
	s_nop 0
	v_max3_f32 v177, v177, v84, v68
	s_nop 0
	v_max3_f32 v177, v177, v85, v69
	s_nop 0
	v_max3_f32 v177, v177, v86, v70
	s_nop 0
	v_max3_f32 v177, v177, v87, v71
	s_nop 0
	v_max3_f32 v177, v177, v88, v72
	s_nop 0
	v_max3_f32 v177, v177, v89, v73
	s_nop 0
	v_max3_f32 v177, v177, v90, v74
	s_nop 0
	v_max3_f32 v177, v177, v91, v75
	s_nop 0
	v_max3_f32 v177, v177, v92, v76
	s_nop 0
	v_max3_f32 v177, v177, v93, v77
	s_nop 0
	v_max3_f32 v177, v177, v94, v78
	s_nop 0
	v_max3_f32 v177, v177, v95, v79
	v_max_f32_e32 v177, v177, v177
	v_mov_b32_e32 v178, v177
	s_nop 1
	v_permlane32_swap_b32_e32 v178, v177
	v_max_f32_e32 v177, v177, v178
	v_mul_f32_e32 v177, 0x3e0293ee, v177
	v_add_f32_e32 v178, 0x41000000, v176
	v_cmp_gt_f32_e32 vcc, v177, v178
	s_cbranch_vccz .LBB0_178
	s_nop 0
	v_cndmask_b32_e32 v177, v176, v177, vcc
	v_sub_f32_e32 v176, v176, v177
	v_exp_f32_e32 v176, v176
	s_nop 0
	v_pk_mul_f32 v[62:63], v[62:63], v[176:177] op_sel_hi:[1,0]
	v_pk_mul_f32 v[60:61], v[60:61], v[176:177] op_sel_hi:[1,0]
	v_pk_mul_f32 v[58:59], v[58:59], v[176:177] op_sel_hi:[1,0]
	v_pk_mul_f32 v[56:57], v[56:57], v[176:177] op_sel_hi:[1,0]
	v_pk_mul_f32 v[54:55], v[54:55], v[176:177] op_sel_hi:[1,0]
	v_pk_mul_f32 v[52:53], v[52:53], v[176:177] op_sel_hi:[1,0]
	v_pk_mul_f32 v[50:51], v[50:51], v[176:177] op_sel_hi:[1,0]
	v_pk_mul_f32 v[48:49], v[48:49], v[176:177] op_sel_hi:[1,0]
	v_pk_mul_f32 v[46:47], v[46:47], v[176:177] op_sel_hi:[1,0]
	v_pk_mul_f32 v[44:45], v[44:45], v[176:177] op_sel_hi:[1,0]
	v_pk_mul_f32 v[42:43], v[42:43], v[176:177] op_sel_hi:[1,0]
	v_pk_mul_f32 v[40:41], v[40:41], v[176:177] op_sel_hi:[1,0]
	v_pk_mul_f32 v[38:39], v[38:39], v[176:177] op_sel_hi:[1,0]
	v_pk_mul_f32 v[36:37], v[36:37], v[176:177] op_sel_hi:[1,0]
	v_pk_mul_f32 v[34:35], v[34:35], v[176:177] op_sel_hi:[1,0]
	v_pk_mul_f32 v[32:33], v[32:33], v[176:177] op_sel_hi:[1,0]
	v_pk_mul_f32 v[30:31], v[30:31], v[176:177] op_sel_hi:[1,0]
	v_pk_mul_f32 v[28:29], v[28:29], v[176:177] op_sel_hi:[1,0]
	v_pk_mul_f32 v[26:27], v[26:27], v[176:177] op_sel_hi:[1,0]
	v_pk_mul_f32 v[24:25], v[24:25], v[176:177] op_sel_hi:[1,0]
	v_pk_mul_f32 v[22:23], v[22:23], v[176:177] op_sel_hi:[1,0]
	v_pk_mul_f32 v[20:21], v[20:21], v[176:177] op_sel_hi:[1,0]
	v_pk_mul_f32 v[18:19], v[18:19], v[176:177] op_sel_hi:[1,0]
	v_pk_mul_f32 v[16:17], v[16:17], v[176:177] op_sel_hi:[1,0]
	v_pk_mul_f32 v[14:15], v[14:15], v[176:177] op_sel_hi:[1,0]
	v_pk_mul_f32 v[12:13], v[12:13], v[176:177] op_sel_hi:[1,0]
	v_pk_mul_f32 v[10:11], v[10:11], v[176:177] op_sel_hi:[1,0]
	v_pk_mul_f32 v[8:9], v[8:9], v[176:177] op_sel_hi:[1,0]
	v_pk_mul_f32 v[6:7], v[6:7], v[176:177] op_sel_hi:[1,0]
	v_pk_mul_f32 v[4:5], v[4:5], v[176:177] op_sel_hi:[1,0]
	v_pk_mul_f32 v[2:3], v[2:3], v[176:177] op_sel_hi:[1,0]
	v_pk_mul_f32 v[0:1], v[0:1], v[176:177] op_sel_hi:[1,0]
	v_mul_f32_e32 v173, v173, v176
	v_mov_b32_e32 v176, v177
; __device__ __forceinline__ void attn_phase(LAS unsigned char* lds, bf16_t* Qb, const bf16_t* KVb, const bf16_t* GZ, const float* sinkp) {
;     ...
;                     float rs = 0.f;
; #pragma unroll
;                     for (int r = 0; r < 16; ++r) { s0[r] = __builtin_amdgcn_exp2f(__builtin_fmaf(s0[r], SC, -m_run)); s1[r] = __builtin_amdgcn_exp2f(__builtin_fmaf(s1[r], SC, -m_run)); rs += s0[r] + s1[r]; }
;                     rs += __shfl_xor(rs, 32);
;                     l_run += rs;
;                     {
;                         bf16x8 pf[4];
; #pragma unroll
;                         for (int c = 0; c < 4; ++c) {
;                             const int s8 = 8 * (c & 1); u32x4 pw;
;                             if (c < 2) { pw.x = cvt_pk_bf16(s0[s8], s0[s8 + 1]); pw.y = cvt_pk_bf16(s0[s8 + 2], s0[s8 + 3]); pw.z = cvt_pk_bf16(s0[s8 + 4], s0[s8 + 5]); pw.w = cvt_pk_bf16(s0[s8 + 6], s0[s8 + 7]); }
;                             else { pw.x = cvt_pk_bf16(s1[s8], s1[s8 + 1]); pw.y = cvt_pk_bf16(s1[s8 + 2], s1[s8 + 3]); pw.z = cvt_pk_bf16(s1[s8 + 4], s1[s8 + 5]); pw.w = cvt_pk_bf16(s1[s8 + 6], s1[s8 + 7]); }
;                             pf[c] = __builtin_bit_cast(bf16x8, pw);
;                         }
;                         s16x4 va[2][4][2];
; #pragma unroll
;                         for (int dt = 0; dt < 4; ++dt) { va[0][dt][0] = __builtin_amdgcn_ds_read_tr16_b64_v4i16((LAS s16x4*)(Vc + vaddr[dt][0])); va[0][dt][1] = __builtin_amdgcn_ds_read_tr16_b64_v4i16((LAS s16x4*)(Vc + vaddr[dt][1])); }
;                         __builtin_amdgcn_sched_barrier(0);
; #pragma unroll
;                         for (int c = 0; c < 4; ++c) {
;                             if (c < 3) {
; #pragma unroll
;                                 for (int dt = 0; dt < 4; ++dt) { va[(c + 1) & 1][dt][0] = __builtin_amdgcn_ds_read_tr16_b64_v4i16((LAS s16x4*)(Vc + vaddr[dt][0] + (c + 1) * 4096)); va[(c + 1) & 1][dt][1] = __builtin_amdgcn_ds_read_tr16_b64_v4i16((LAS s16x4*)(Vc + vaddr[dt][1] + (c + 1) * 4096)); }
;                             }
;                             __builtin_amdgcn_sched_barrier(0);
; #pragma unroll
;                             for (int dt = 0; dt < 4; ++dt) {
;                                 const s16x4 a0 = va[c & 1][dt][0], a1 = va[c & 1][dt][1];
;                                 const bf16x8 a = {a0[0], a0[1], a0[2], a0[3], a1[0], a1[1], a1[2], a1[3]};
.LBB0_178:
	v_fma_f32 v80, v80, s82, -v176
	v_fma_f32 v64, v64, s82, -v176
	v_exp_f32_e32 v177, v80
	v_exp_f32_e32 v178, v64
	v_fma_f32 v80, v81, s82, -v176
	v_fma_f32 v65, v65, s82, -v176
	v_exp_f32_e32 v179, v80
	v_exp_f32_e32 v180, v65
	v_add_f32_e32 v64, v177, v178
	v_add_f32_e32 v64, 0, v64
	v_add_u32_e32 v202, s3, v163
	v_add_f32_e32 v65, v179, v180
	v_add_f32_e32 v64, v65, v64
	v_fma_f32 v65, v82, s82, -v176
	v_exp_f32_e32 v181, v65
	v_fma_f32 v65, v66, s82, -v176
	v_exp_f32_e32 v182, v65
	v_add_u32_e32 v203, s3, v164
	v_add_u32_e32 v204, s3, v165
	v_add_u32_e32 v205, s3, v166
	v_add_f32_e32 v65, v181, v182
	v_add_f32_e32 v64, v65, v64
	v_fma_f32 v65, v83, s82, -v176
	v_exp_f32_e32 v66, v65
	v_fma_f32 v65, v67, s82, -v176
	v_exp_f32_e32 v183, v65
	v_add_u32_e32 v206, s3, v167
	v_add_u32_e32 v207, s3, v168
	v_add_f32_e32 v65, v66, v183
	v_add_f32_e32 v64, v65, v64
	v_fma_f32 v65, v84, s82, -v176
	v_exp_f32_e32 v67, v65
	v_fma_f32 v65, v68, s82, -v176
	v_exp_f32_e32 v184, v65
	s_nop 0
	v_add_f32_e32 v65, v67, v184
	v_add_f32_e32 v64, v65, v64
	v_fma_f32 v65, v85, s82, -v176
	v_exp_f32_e32 v185, v65
	v_fma_f32 v65, v69, s82, -v176
	v_exp_f32_e32 v186, v65
	s_nop 0
	v_add_f32_e32 v65, v185, v186
	v_add_f32_e32 v82, v65, v64
	v_fma_f32 v64, v86, s82, -v176
	v_exp_f32_e32 v69, v64
	v_fma_f32 v64, v70, s82, -v176
	v_exp_f32_e32 v81, v64
	v_fma_f32 v64, v87, s82, -v176
	v_exp_f32_e32 v68, v64
	v_fma_f32 v64, v71, s82, -v176
	v_exp_f32_e32 v80, v64
	s_nop 0
	v_pk_add_f32 v[64:65], v[68:69], v[80:81]
	s_nop 0
	v_add_f32_e32 v65, v65, v82
	v_add_f32_e32 v84, v64, v65
	v_fma_f32 v64, v88, s82, -v176
	v_exp_f32_e32 v71, v64
	v_fma_f32 v64, v72, s82, -v176
	v_exp_f32_e32 v83, v64
	v_fma_f32 v64, v89, s82, -v176
	v_exp_f32_e32 v70, v64
	v_fma_f32 v64, v73, s82, -v176
	v_exp_f32_e32 v82, v64
	s_nop 0
	v_pk_add_f32 v[64:65], v[70:71], v[82:83]
	s_nop 0
	v_add_f32_e32 v65, v65, v84
	v_add_f32_e32 v86, v64, v65
	v_fma_f32 v64, v90, s82, -v176
	v_exp_f32_e32 v73, v64
	v_fma_f32 v64, v74, s82, -v176
	v_exp_f32_e32 v85, v64
	v_fma_f32 v64, v91, s82, -v176
	v_exp_f32_e32 v72, v64
	v_fma_f32 v64, v75, s82, -v176
	v_exp_f32_e32 v84, v64
	s_nop 0
	v_pk_add_f32 v[64:65], v[72:73], v[84:85]
	s_nop 0
	v_add_f32_e32 v65, v65, v86
	v_add_f32_e32 v88, v64, v65
	v_fma_f32 v64, v92, s82, -v176
	v_exp_f32_e32 v75, v64
	v_fma_f32 v64, v76, s82, -v176
	v_exp_f32_e32 v87, v64
	v_fma_f32 v64, v93, s82, -v176
	v_exp_f32_e32 v74, v64
	v_fma_f32 v64, v77, s82, -v176
	v_exp_f32_e32 v86, v64
	s_nop 0
	v_pk_add_f32 v[64:65], v[74:75], v[86:87]
	s_nop 0
	v_add_f32_e32 v65, v65, v88
	v_add_f32_e32 v90, v64, v65
	v_fma_f32 v64, v94, s82, -v176
	v_exp_f32_e32 v77, v64
	v_fma_f32 v64, v78, s82, -v176
	v_exp_f32_e32 v89, v64
	v_fma_f32 v64, v95, s82, -v176
	v_exp_f32_e32 v76, v64
	v_fma_f32 v64, v79, s82, -v176
	v_exp_f32_e32 v88, v64
	s_nop 0
	v_pk_add_f32 v[64:65], v[76:77], v[88:89]
	s_nop 0
	v_add_f32_e32 v65, v65, v90
	v_add_f32_e32 v64, v64, v65
	v_mov_b32_e32 v65, v64
	s_nop 1
	v_permlane32_swap_b32_e32 v65, v64
	v_add_f32_e32 v187, v64, v65
	v_cvt_pk_bf16_f32 v64, v177, v179
	v_cvt_pk_bf16_f32 v65, v181, v66
	v_cvt_pk_bf16_f32 v66, v67, v185
	v_cvt_pk_bf16_f32 v67, v69, v68
	v_cvt_pk_bf16_f32 v68, v71, v70
	v_cvt_pk_bf16_f32 v69, v73, v72
	v_cvt_pk_bf16_f32 v70, v75, v74
	v_cvt_pk_bf16_f32 v71, v77, v76
	v_cvt_pk_bf16_f32 v72, v178, v180
	v_cvt_pk_bf16_f32 v73, v182, v183
	v_cvt_pk_bf16_f32 v74, v184, v186
	v_add_u32_e32 v177, s3, v161
	v_add_u32_e32 v186, s3, v162
	v_cvt_pk_bf16_f32 v75, v81, v80
	v_cvt_pk_bf16_f32 v76, v83, v82
	v_cvt_pk_bf16_f32 v77, v85, v84
	v_cvt_pk_bf16_f32 v78, v87, v86
	v_cvt_pk_bf16_f32 v79, v89, v88
	s_waitcnt lgkmcnt(14)
	v_mfma_f32_32x32x16_bf16 v[48:63], v[208:211], v[64:67], v[48:63]
	s_waitcnt lgkmcnt(12)
	v_mfma_f32_32x32x16_bf16 v[32:47], v[212:215], v[64:67], v[32:47]
	s_waitcnt lgkmcnt(10)
	v_mfma_f32_32x32x16_bf16 v[16:31], v[216:219], v[64:67], v[16:31]
	s_waitcnt lgkmcnt(8)
	v_mfma_f32_32x32x16_bf16 v[0:15], v[228:231], v[64:67], v[0:15]
	ds_read_b64_tr_b16 v[64:65], v177 offset:24576
	ds_read_b64_tr_b16 v[66:67], v186 offset:24576
	ds_read_b64_tr_b16 v[80:81], v202 offset:24576
	ds_read_b64_tr_b16 v[82:83], v203 offset:24576
	ds_read_b64_tr_b16 v[84:85], v204 offset:24576
	ds_read_b64_tr_b16 v[86:87], v205 offset:24576
	ds_read_b64_tr_b16 v[88:89], v206 offset:24576
	ds_read_b64_tr_b16 v[90:91], v207 offset:24576
	s_waitcnt lgkmcnt(14)
	v_mfma_f32_32x32x16_bf16 v[48:63], v[238:241], v[68:71], v[48:63]
	s_waitcnt lgkmcnt(12)
	v_mfma_f32_32x32x16_bf16 v[32:47], v[242:245], v[68:71], v[32:47]
	s_waitcnt lgkmcnt(10)
	v_mfma_f32_32x32x16_bf16 v[16:31], v[246:249], v[68:71], v[16:31]
	s_waitcnt lgkmcnt(8)
	v_mfma_f32_32x32x16_bf16 v[0:15], v[250:253], v[68:71], v[0:15]
	ds_read_b64_tr_b16 v[68:69], v177 offset:28672
	ds_read_b64_tr_b16 v[70:71], v186 offset:28672
	ds_read_b64_tr_b16 v[92:93], v202 offset:28672
	ds_read_b64_tr_b16 v[94:95], v203 offset:28672
	ds_read_b64_tr_b16 v[178:179], v204 offset:28672
	ds_read_b64_tr_b16 v[180:181], v205 offset:28672
	ds_read_b64_tr_b16 v[182:183], v206 offset:28672
	ds_read_b64_tr_b16 v[184:185], v207 offset:28672
	s_waitcnt lgkmcnt(14)
	v_mfma_f32_32x32x16_bf16 v[48:63], v[64:67], v[72:75], v[48:63]
	s_waitcnt lgkmcnt(12)
	v_mfma_f32_32x32x16_bf16 v[32:47], v[80:83], v[72:75], v[32:47]
	s_waitcnt lgkmcnt(10)
	v_mfma_f32_32x32x16_bf16 v[16:31], v[84:87], v[72:75], v[16:31]
	s_waitcnt lgkmcnt(8)
	v_mfma_f32_32x32x16_bf16 v[0:15], v[88:91], v[72:75], v[0:15]
	s_waitcnt lgkmcnt(6)
	v_mfma_f32_32x32x16_bf16 v[48:63], v[68:71], v[76:79], v[48:63]
	s_waitcnt lgkmcnt(4)
	v_mfma_f32_32x32x16_bf16 v[32:47], v[92:95], v[76:79], v[32:47]
	s_waitcnt lgkmcnt(2)
	v_mfma_f32_32x32x16_bf16 v[16:31], v[178:181], v[76:79], v[16:31]
	s_waitcnt lgkmcnt(0)
	v_mfma_f32_32x32x16_bf16 v[0:15], v[182:185], v[76:79], v[0:15]
	v_add_f32_e32 v173, v173, v187
